# software-prefetch K/V one block ahead in MT3 sample-B attention loop (K via spare regs + copy, V issued after last PV MFMA)
# baseline (speedup 1.0000x reference)
; DI int otid() { int t = threadIdx.x; asm volatile("" : "+v"(t)); return t; }
; template <int HD, int BIAS, bool FULL>
; DI void attn_block(const bf16_t* Kb, int ktb, const bf16_t* Vb, int vtb, int koff, int kpos0, int qp, float slope, const float* rel,
;                    const bf16x8 (&qf)[HD / 16], f32x16 (&o)[HD / 32], float& m, float& l) {
;     ...
;     bf16x8 kreg[NKT][KSQ];
; #pragma unroll
;     for (int kt = 0; kt < NKT; ++kt)
; #pragma unroll
;         for (int ks = 0; ks < KSQ; ++ks) kreg[kt][ks] = *(const bf16x8*)(Kb + (size_t)kt * ktb + ks * 512 + lane * 8);
;     constexpr int NS = FULL ? 4 : 1;
;     bf16x8 vreg[DT][NS];
;     auto loadV = [&]() {
; #pragma unroll
;         for (int si = 0; si < NS; ++si)
; #pragma unroll
;             for (int dt = 0; dt < DT; ++dt) { const int s = FULL ? si : s0; vreg[dt][si] = *(const bf16x8*)(Vb + (size_t)(s >> 1) * vtb + dt * 1024 + (s & 1) * 512 + lane * 8); }
;     };
;     if (VTOP) loadV();
; template <int HD, int BIAS> ...
;     ...
;     const int lane = otid() & 63, r = lane & 31, h = lane >> 5;
;     const int qr = r < nq ? r : nq - 1;
;     bf16x8 qf[KSQ];
; #pragma unroll
;     for (int ks = 0; ks < KSQ; ++ks) qf[ks] = *(const bf16x8*)(Q + (size_t)qr * qstride + ks * 16 + 8 * h);
;     f32x16 o[DT];
; #pragma unroll
;     for (int dt = 0; dt < DT; ++dt)
; #pragma unroll
;         for (int i = 0; i < 16; ++i) o[dt][i] = 0.f;
;     float m = m0, l = h == 0 ? l0 : 0.f;
;     const int qp = qpos0 + qr;
; #pragma unroll 1
;     for (int blk = 0; blk < nb1; ++blk)
;         attn_block<HD, BIAS, true>(K1 + (size_t)(2 * blk) * ktb1, ktb1, V1 + (size_t)(2 * blk) * vtb1, vtb1, 0, pos1 + blk * 64, qp, slope, rel, qf, o, m, l);
.LBB0_326:
	s_cmp_gt_i32 s75, 31
	s_cbranch_scc0 .LBB0_349
	s_bfe_u32 s96, s75, 0x10003
	s_add_i32 s8, s72, s96
	s_or_b32 s0, s96, s74
	s_ashr_i32 s9, s8, 31
	s_lshl_b32 s1, s0, 4
	s_lshl_b32 s97, s96, 4
	s_mul_i32 s0, s0, 0x2c000
	s_mul_hi_i32 s1, s1, 0x2c00
	s_add_u32 s53, s19, s0
	v_readlane_b32 s0, v253, 15
	s_addc_u32 s37, s0, s1
	s_and_b32 s0, s75, 0x7ffffff0
	s_cmp_lg_u32 s0, 32
	s_cbranch_scc0 .LBB0_350
	s_lshl_b64 s[0:1], s[8:9], 19
	s_waitcnt lgkmcnt(0)
	v_mov_b32_e32 v0, v176
	s_add_u32 s2, s88, s0
	s_addc_u32 s3, s89, s1
	s_waitcnt vmcnt(0)
	v_and_b32_e32 v115, 31, v0
	s_lshl_b32 s70, s56, 1
	v_min_u32_e32 v117, 15, v115
	s_add_u32 s0, s53, s70
	v_bfe_u32 v114, v0, 5, 1
	v_mul_u32_u24_e32 v0, 0x1600, v117
	s_addc_u32 s1, s37, 0
	v_lshlrev_b32_e32 v0, 1, v0
	v_lshl_add_u64 v[2:3], s[0:1], 0, v[0:1]
	v_lshlrev_b32_e32 v0, 4, v114
	v_lshl_add_u64 v[2:3], v[2:3], 0, v[0:1]
	s_mov_b64 s[0:1], 0xb000400
	v_lshl_add_u64 v[4:5], v[2:3], 0, s[0:1]
	v_add_co_u32_e32 v2, vcc, 0xb000000, v2
	v_mov_b32_e32 v59, 0
	s_nop 0
	v_addc_co_u32_e32 v3, vcc, 0, v3, vcc
	global_load_dwordx4 v[74:77], v[4:5], off offset:32
	global_load_dwordx4 v[66:69], v[4:5], off offset:64
	global_load_dwordx4 v[78:81], v[2:3], off offset:1024
	global_load_dwordx4 v[70:73], v[4:5], off offset:96
	v_sub_u32_e32 v118, 0xfffffe00, v117
	v_mov_b32_e32 v58, 0xf149f2ca
	s_mov_b64 s[0:1], 0
	v_mov_b32_e32 v2, 0
	v_mov_b32_e32 v3, v59
	v_mov_b32_e32 v4, v59
	v_mov_b32_e32 v5, v59
	v_mov_b32_e32 v6, v59
	v_mov_b32_e32 v7, v59
	v_mov_b32_e32 v8, v59
	v_mov_b32_e32 v9, v59
	v_mov_b32_e32 v10, v59
	v_mov_b32_e32 v11, v59
	v_mov_b32_e32 v12, v59
	v_mov_b32_e32 v13, v59
	v_mov_b32_e32 v14, v59
	v_mov_b32_e32 v15, v59
	v_mov_b32_e32 v16, v59
	v_mov_b32_e32 v17, v59
	v_mov_b32_e32 v18, 0
	v_mov_b32_e32 v19, v59
	v_mov_b32_e32 v20, v59
	v_mov_b32_e32 v21, v59
	v_mov_b32_e32 v22, v59
	v_mov_b32_e32 v23, v59
	v_mov_b32_e32 v24, v59
	v_mov_b32_e32 v25, v59
	v_mov_b32_e32 v26, v59
	v_mov_b32_e32 v27, v59
	v_mov_b32_e32 v28, v59
	v_mov_b32_e32 v29, v59
	v_mov_b32_e32 v30, v59
	v_mov_b32_e32 v31, v59
	v_mov_b32_e32 v32, v59
	v_mov_b32_e32 v33, v59
	v_and_b32_e32 v184, 63, v176
	v_lshlrev_b32_e32 v184, 4, v184
	s_add_u32 s28, s2, 0x18406000
	s_addc_u32 s29, s3, 0
	global_load_dwordx4 v[224:227], v184, s[28:29]
	global_load_dwordx4 v[228:231], v184, s[28:29] offset:1024
	global_load_dwordx4 v[232:235], v184, s[28:29] offset:2048
	global_load_dwordx4 v[236:239], v184, s[28:29] offset:3072
	s_add_u32 s28, s28, 0x8000
	s_addc_u32 s29, s29, 0
	global_load_dwordx4 v[240:243], v184, s[28:29]
	global_load_dwordx4 v[244:247], v184, s[28:29] offset:1024
	global_load_dwordx4 v[248:251], v184, s[28:29] offset:2048
	global_load_dwordx4 v[180:183], v184, s[28:29] offset:3072
	s_add_u32 s28, s2, 0x18806000
	s_addc_u32 s29, s3, 0
	global_load_dwordx4 v[110:113], v184, s[28:29]
	global_load_dwordx4 v[102:105], v184, s[28:29] offset:1024
	global_load_dwordx4 v[106:109], v184, s[28:29] offset:2048
	global_load_dwordx4 v[98:101], v184, s[28:29] offset:3072
	s_add_u32 s28, s28, 0x8000
	s_addc_u32 s29, s29, 0
	global_load_dwordx4 v[94:97], v184, s[28:29]
	global_load_dwordx4 v[86:89], v184, s[28:29] offset:1024
	global_load_dwordx4 v[90:93], v184, s[28:29] offset:2048
	global_load_dwordx4 v[82:85], v184, s[28:29] offset:3072
.LBB0_329:
	v_lshrrev_b32_e32 v0, 3, v176
	v_and_b32_e32 v0, 4, v0
	v_add_u32_e32 v120, v118, v0
	s_waitcnt vmcnt(8)
	v_mov_b64_e32 v[34:35], v[224:225]
	v_mov_b64_e32 v[36:37], v[226:227]
	v_mov_b64_e32 v[38:39], v[228:229]
	v_mov_b64_e32 v[40:41], v[230:231]
	v_mov_b64_e32 v[42:43], v[232:233]
	v_mov_b64_e32 v[44:45], v[234:235]
	v_mov_b64_e32 v[46:47], v[236:237]
	v_mov_b64_e32 v[48:49], v[238:239]
	v_mov_b64_e32 v[122:123], v[240:241]
	v_mov_b64_e32 v[124:125], v[242:243]
	v_mov_b64_e32 v[126:127], v[244:245]
	v_mov_b64_e32 v[128:129], v[246:247]
	v_mov_b64_e32 v[130:131], v[248:249]
	v_mov_b64_e32 v[132:133], v[250:251]
	v_mov_b64_e32 v[134:135], v[180:181]
	v_mov_b64_e32 v[136:137], v[182:183]
	s_add_u32 s28, s2, s0
	s_addc_u32 s29, s3, s1
	s_add_u32 s28, s28, 0x18416000
	s_addc_u32 s29, s29, 0
	global_load_dwordx4 v[224:227], v184, s[28:29]
	global_load_dwordx4 v[228:231], v184, s[28:29] offset:1024
	global_load_dwordx4 v[232:235], v184, s[28:29] offset:2048
	global_load_dwordx4 v[236:239], v184, s[28:29] offset:3072
	s_add_u32 s28, s28, 0x8000
	s_addc_u32 s29, s29, 0
	global_load_dwordx4 v[240:243], v184, s[28:29]
	global_load_dwordx4 v[244:247], v184, s[28:29] offset:1024
	global_load_dwordx4 v[248:251], v184, s[28:29] offset:2048
	global_load_dwordx4 v[180:183], v184, s[28:29] offset:3072
	v_mov_b32_e32 v121, v58
	v_mov_b32_e32 v119, v59
	v_mfma_f32_32x32x16_f16 v[50:65], v[34:37], v[78:81], 0
	v_mfma_f32_32x32x16_f16 v[50:65], v[38:41], v[74:77], v[50:65]
	v_mfma_f32_32x32x16_f16 v[50:65], v[42:45], v[66:69], v[50:65]
	v_mfma_f32_32x32x16_f16 v[50:65], v[46:49], v[70:73], v[50:65]
	v_mfma_f32_32x32x16_f16 v[34:49], v[122:125], v[78:81], 0
	v_mfma_f32_32x32x16_f16 v[34:49], v[126:129], v[74:77], v[34:49]
	v_mfma_f32_32x32x16_f16 v[34:49], v[130:133], v[66:69], v[34:49]
	v_mfma_f32_32x32x16_f16 v[34:49], v[134:137], v[70:73], v[34:49]
	v_add_u32_e32 v142, 2, v120
	v_med3_i32 v142, v142, s45, v186
	v_lshl_add_u32 v142, v142, 2, s61
	ds_read_b32 v142, v142 offset:1024
	v_med3_i32 v143, v120, s45, v186
	v_lshl_add_u32 v143, v143, 2, s61
	ds_read_b32 v143, v143 offset:1024
	v_add_u32_e32 v144, 3, v120
	v_med3_i32 v144, v144, s45, v186
	v_lshl_add_u32 v144, v144, 2, s61
	ds_read_b32 v144, v144 offset:1024
	v_add_u32_e32 v145, 8, v120
	v_med3_i32 v145, v145, s45, v186
; DI int crow(int i, int h) { return (i & 3) + 8 * (i >> 2) + 4 * h; }
; template <int HD, int BIAS, bool FULL>
; DI void attn_block(const bf16_t* Kb, int ktb, const bf16_t* Vb, int vtb, int koff, int kpos0, int qp, float slope, const float* rel,
;                    const bf16x8 (&qf)[HD / 16], f32x16 (&o)[HD / 32], float& m, float& l) {
;     ...
;     float mx = -1e30f;
; #pragma unroll
;     for (int kt = 0; kt < NKT; ++kt)
; #pragma unroll
;         for (int i = 0; i < 16; ++i) {
;             const int key = kt * 32 + crow(i, h);
;             float s = st[kt][i];
;             const int dk = dq + (kt * 32 + (i & 3) + 8 * (i >> 2));
;             if (BIAS == 1) s -= slope * (float)(dk < 0 ? -dk : dk);
;             if (BIAS == 2) { int d = dk < -256 ? -256 : (dk > 256 ? 256 : dk); s += rel[d + 256]; }
;             if (!FULL) { if (key < kbeg || key >= kend) s = -1e30f; }
;             st[kt][i] = s; mx = fmaxf(mx, s);
;         }
;     mx = fmaxf(mx, __shfl_xor(mx, 32));
	v_lshl_add_u32 v145, v145, 2, s61
	ds_read_b32 v145, v145 offset:1024
	v_add_u32_e32 v146, 9, v120
	v_med3_i32 v146, v146, s45, v186
	v_lshl_add_u32 v146, v146, 2, s61
	ds_read_b32 v146, v146 offset:1024
	v_add_u32_e32 v147, 10, v120
	v_med3_i32 v147, v147, s45, v186
	v_lshl_add_u32 v147, v147, 2, s61
	ds_read_b32 v147, v147 offset:1024
	v_add_u32_e32 v148, 11, v120
	v_med3_i32 v148, v148, s45, v186
	v_lshl_add_u32 v148, v148, 2, s61
	ds_read_b32 v148, v148 offset:1024
	v_add_u32_e32 v149, 16, v120
	v_med3_i32 v149, v149, s45, v186
	v_lshl_add_u32 v149, v149, 2, s61
	ds_read_b32 v149, v149 offset:1024
	v_add_u32_e32 v150, 17, v120
	v_med3_i32 v150, v150, s45, v186
	v_lshl_add_u32 v150, v150, 2, s61
	ds_read_b32 v150, v150 offset:1024
	v_add_u32_e32 v151, 1, v120
	v_med3_i32 v151, v151, s45, v186
	v_lshl_add_u32 v151, v151, 2, s61
	v_add_u32_e32 v152, 18, v120
	v_med3_i32 v152, v152, s45, v186
	v_lshl_add_u32 v152, v152, 2, s61
	ds_read_b32 v151, v151 offset:1024
	ds_read_b32 v152, v152 offset:1024
	v_add_u32_e32 v153, 19, v120
	v_med3_i32 v153, v153, s45, v186
	v_lshl_add_u32 v153, v153, 2, s61
	ds_read_b32 v153, v153 offset:1024
	v_add_u32_e32 v154, 24, v120
	v_med3_i32 v154, v154, s45, v186
	v_lshl_add_u32 v154, v154, 2, s61
	ds_read_b32 v154, v154 offset:1024
	v_add_u32_e32 v155, 25, v120
	v_med3_i32 v155, v155, s45, v186
	v_lshl_add_u32 v155, v155, 2, s61
	ds_read_b32 v155, v155 offset:1024
	v_add_u32_e32 v156, 26, v120
	v_med3_i32 v156, v156, s45, v186
	v_lshl_add_u32 v156, v156, 2, s61
	ds_read_b32 v156, v156 offset:1024
	v_add_u32_e32 v157, 27, v120
	v_med3_i32 v157, v157, s45, v186
	v_lshl_add_u32 v157, v157, 2, s61
	ds_read_b32 v157, v157 offset:1024
	v_add_u32_e32 v158, 32, v120
	v_med3_i32 v158, v158, s45, v186
	v_lshl_add_u32 v158, v158, 2, s61
	ds_read_b32 v158, v158 offset:1024
	v_add_u32_e32 v159, 33, v120
	v_med3_i32 v159, v159, s45, v186
	v_lshl_add_u32 v159, v159, 2, s61
	ds_read_b32 v159, v159 offset:1024
	v_add_u32_e32 v160, 34, v120
	v_med3_i32 v160, v160, s45, v186
	v_lshl_add_u32 v160, v160, 2, s61
	ds_read_b32 v160, v160 offset:1024
	v_add_u32_e32 v161, 35, v120
	v_med3_i32 v161, v161, s45, v186
	v_lshl_add_u32 v161, v161, 2, s61
	ds_read_b32 v161, v161 offset:1024
	v_add_u32_e32 v162, 40, v120
	v_med3_i32 v162, v162, s45, v186
	v_lshl_add_u32 v162, v162, 2, s61
	ds_read_b32 v162, v162 offset:1024
	v_add_u32_e32 v163, 41, v120
	v_med3_i32 v163, v163, s45, v186
	v_lshl_add_u32 v163, v163, 2, s61
	ds_read_b32 v163, v163 offset:1024
	v_add_u32_e32 v164, 42, v120
	v_med3_i32 v164, v164, s45, v186
	v_lshl_add_u32 v164, v164, 2, s61
	ds_read_b32 v164, v164 offset:1024
	v_add_u32_e32 v165, 43, v120
	v_med3_i32 v165, v165, s45, v186
	v_lshl_add_u32 v165, v165, 2, s61
	ds_read_b32 v165, v165 offset:1024
	v_add_u32_e32 v166, 48, v120
	v_med3_i32 v166, v166, s45, v186
	v_lshl_add_u32 v166, v166, 2, s61
	ds_read_b32 v166, v166 offset:1024
	v_add_u32_e32 v167, 49, v120
	v_med3_i32 v167, v167, s45, v186
	v_lshl_add_u32 v167, v167, 2, s61
	ds_read_b32 v167, v167 offset:1024
	v_add_u32_e32 v168, 50, v120
	v_med3_i32 v168, v168, s45, v186
	v_lshl_add_u32 v168, v168, 2, s61
	ds_read_b32 v168, v168 offset:1024
	v_add_u32_e32 v169, 51, v120
	v_med3_i32 v169, v169, s45, v186
	v_lshl_add_u32 v169, v169, 2, s61
	ds_read_b32 v169, v169 offset:1024
	v_add_u32_e32 v170, 56, v120
	v_med3_i32 v170, v170, s45, v186
	v_lshl_add_u32 v170, v170, 2, s61
	ds_read_b32 v170, v170 offset:1024
	v_add_u32_e32 v171, 57, v120
	v_med3_i32 v171, v171, s45, v186
	v_lshl_add_u32 v171, v171, 2, s61
	ds_read_b32 v171, v171 offset:1024
	v_add_u32_e32 v172, 58, v120
	v_med3_i32 v172, v172, s45, v186
	v_lshl_add_u32 v172, v172, 2, s61
	ds_read_b32 v172, v172 offset:1024
	v_add_u32_e32 v173, 59, v120
	v_med3_i32 v173, v173, s45, v186
	v_lshl_add_u32 v173, v173, 2, s61
	ds_read_b32 v173, v173 offset:1024
	s_waitcnt lgkmcnt(0)
	v_cmp_lt_i32_e32 vcc, v188, v189
	v_add_f32_e32 v52, v52, v142
	s_add_u32 s0, s0, 0x10000
	s_addc_u32 s1, s1, 0
	v_add_u32_e32 v118, 64, v118
	s_cmp_eq_u32 s0, 0x80000
	v_add_f32_e32 v53, v53, v144
	v_add_f32_e32 v54, v54, v145
	v_add_f32_e32 v55, v55, v146
	v_add_f32_e32 v56, v56, v147
	v_add_f32_e32 v57, v57, v148
	v_add_f32_e32 v122, v58, v149
	v_add_f32_e32 v50, v50, v143
	v_add_f32_e32 v59, v59, v150
	v_add_f32_e32 v51, v51, v151
	v_add_f32_e32 v60, v60, v152
	v_max3_f32 v0, v50, s46, v51
	v_max3_f32 v0, v0, v52, v53
	v_max3_f32 v0, v0, v54, v55
	v_max3_f32 v0, v0, v56, v57
	v_add_f32_e32 v61, v61, v153
	v_max3_f32 v0, v0, v122, v59
	v_max3_f32 v0, v0, v60, v61
	v_add_f32_e32 v62, v62, v154
	v_add_f32_e32 v63, v63, v155
	v_max3_f32 v0, v0, v62, v63
	v_add_f32_e32 v64, v64, v156
	v_add_f32_e32 v65, v65, v157
	v_max3_f32 v0, v0, v64, v65
	v_add_f32_e32 v34, v34, v158
	v_add_f32_e32 v35, v35, v159
	v_max3_f32 v0, v0, v34, v35
	v_add_f32_e32 v36, v36, v160
	v_add_f32_e32 v37, v37, v161
	v_max3_f32 v0, v0, v36, v37
	v_add_f32_e32 v38, v38, v162
	v_add_f32_e32 v39, v39, v163
	v_max3_f32 v0, v0, v38, v39
	v_add_f32_e32 v40, v40, v164
	v_add_f32_e32 v41, v41, v165
	v_max3_f32 v0, v0, v40, v41
	v_add_f32_e32 v42, v42, v166
	v_add_f32_e32 v43, v43, v167
	v_max3_f32 v0, v0, v42, v43
	v_add_f32_e32 v44, v44, v168
	v_add_f32_e32 v45, v45, v169
	v_max3_f32 v0, v0, v44, v45
	v_add_f32_e32 v46, v46, v170
	v_add_f32_e32 v47, v47, v171
	v_max3_f32 v0, v0, v46, v47
	v_add_f32_e32 v48, v48, v172
	v_add_f32_e32 v49, v49, v173
	v_max3_f32 v58, v0, v48, v49
	v_cndmask_b32_e32 v0, v187, v188, vcc
	v_lshlrev_b32_e32 v0, 2, v0
	ds_bpermute_b32 v120, v0, v58
	s_waitcnt lgkmcnt(0)
; #define MFMA32(a, b, c) __builtin_amdgcn_mfma_f32_32x32x16_f16((a), (b), (c), 0, 0, 0)
; DI unsigned pk2(float lo, float hi) { f32x2 v = {lo, hi}; bf2_t b = __builtin_convertvector(v, bf2_t); return __builtin_bit_cast(unsigned, b); }
; template <int HD, int BIAS, bool FULL>
; DI void attn_block(const bf16_t* Kb, int ktb, const bf16_t* Vb, int vtb, int koff, int kpos0, int qp, float slope, const float* rel,
;                    const bf16x8 (&qf)[HD / 16], f32x16 (&o)[HD / 32], float& m, float& l) {
;     ...
;     mx = fmaxf(mx, __shfl_xor(mx, 32));
;     const float mn = fmaxf(m, mx);
;     const float alpha = __builtin_amdgcn_exp2f((m - mn) * LOG2E);
;     m = mn;
;     float ps = 0.f;
; #pragma unroll
;     for (int kt = 0; kt < NKT; ++kt)
; #pragma unroll
;         for (int i = 0; i < 16; ++i) { const float pv = __builtin_amdgcn_exp2f((st[kt][i] - mn) * LOG2E); st[kt][i] = pv; ps += pv; }
;     l = l * alpha + ps;
; #pragma unroll
;     for (int dt = 0; dt < DT; ++dt)
; #pragma unroll
;         for (int i = 0; i < 16; ++i) o[dt][i] *= alpha;
; #pragma unroll
;     for (int si = 0; si < NS; ++si) {
;         u32x4 pw;
;         if (FULL) { const int kt = si >> 1, b0 = (si & 1) * 8; pw = (u32x4){pk2(st[kt][b0], st[kt][b0 + 1]), pk2(st[kt][b0 + 2], st[kt][b0 + 3]), pk2(st[kt][b0 + 4], st[kt][b0 + 5]), pk2(st[kt][b0 + 6], st[kt][b0 + 7])}; }
;         else {
;             const u32x4 lo = {pk2(st[0][0], st[0][1]), pk2(st[0][2], st[0][3]), pk2(st[0][4], st[0][5]), pk2(st[0][6], st[0][7])};
;             const u32x4 hi = {pk2(st[0][8], st[0][9]), pk2(st[0][10], st[0][11]), pk2(st[0][12], st[0][13]), pk2(st[0][14], st[0][15])};
;             pw = (s0 & 1) ? hi : lo;
;         }
;         const bf16x8 pf = __builtin_bit_cast(bf16x8, pw);
; #pragma unroll
;         for (int dt = 0; dt < DT; ++dt) o[dt] = MFMA32(vreg[dt][si], pf, o[dt]);
;     }
	v_max3_f32 v58, v121, v58, v120
	v_sub_f32_e32 v50, v50, v58
	v_mul_f32_e32 v50, 0x3fb8aa3b, v50
	v_sub_f32_e32 v51, v51, v58
	v_exp_f32_e32 v50, v50
	v_mul_f32_e32 v51, 0x3fb8aa3b, v51
	v_sub_f32_e32 v52, v52, v58
	v_exp_f32_e32 v51, v51
	v_mul_f32_e32 v52, 0x3fb8aa3b, v52
	v_sub_f32_e32 v53, v53, v58
	v_sub_f32_e32 v35, v35, v58
	v_exp_f32_e32 v52, v52
	v_mul_f32_e32 v53, 0x3fb8aa3b, v53
	v_sub_f32_e32 v54, v54, v58
	v_mul_f32_e32 v35, 0x3fb8aa3b, v35
	v_exp_f32_e32 v53, v53
	v_mul_f32_e32 v54, 0x3fb8aa3b, v54
	v_sub_f32_e32 v55, v55, v58
	v_exp_f32_e32 v124, v35
	v_sub_f32_e32 v35, v36, v58
	v_sub_f32_e32 v120, v121, v58
	v_add_f32_e32 v121, 0, v50
	v_exp_f32_e32 v54, v54
	v_mul_f32_e32 v55, 0x3fb8aa3b, v55
	v_sub_f32_e32 v56, v56, v58
	v_mul_f32_e32 v35, 0x3fb8aa3b, v35
	v_add_f32_e32 v121, v51, v121
	v_exp_f32_e32 v55, v55
	v_mul_f32_e32 v56, 0x3fb8aa3b, v56
	v_sub_f32_e32 v57, v57, v58
	v_exp_f32_e32 v125, v35
	v_sub_f32_e32 v35, v37, v58
	v_add_f32_e32 v121, v52, v121
	v_exp_f32_e32 v56, v56
	v_mul_f32_e32 v57, 0x3fb8aa3b, v57
	v_sub_f32_e32 v122, v122, v58
	v_mul_f32_e32 v35, 0x3fb8aa3b, v35
	v_add_f32_e32 v121, v53, v121
	v_exp_f32_e32 v57, v57
	v_mul_f32_e32 v122, 0x3fb8aa3b, v122
	v_sub_f32_e32 v59, v59, v58
	v_exp_f32_e32 v126, v35
	v_sub_f32_e32 v35, v38, v58
	v_add_f32_e32 v121, v54, v121
	v_exp_f32_e32 v122, v122
	v_mul_f32_e32 v59, 0x3fb8aa3b, v59
	v_sub_f32_e32 v60, v60, v58
	v_mul_f32_e32 v35, 0x3fb8aa3b, v35
	v_add_f32_e32 v121, v55, v121
	v_exp_f32_e32 v123, v59
	v_mul_f32_e32 v60, 0x3fb8aa3b, v60
	v_sub_f32_e32 v61, v61, v58
	v_exp_f32_e32 v38, v35
	v_sub_f32_e32 v35, v39, v58
	v_add_f32_e32 v121, v56, v121
	v_exp_f32_e32 v60, v60
	v_mul_f32_e32 v61, 0x3fb8aa3b, v61
	v_sub_f32_e32 v62, v62, v58
	v_mul_f32_e32 v35, 0x3fb8aa3b, v35
	v_add_f32_e32 v121, v57, v121
	v_exp_f32_e32 v61, v61
	v_mul_f32_e32 v62, 0x3fb8aa3b, v62
	v_sub_f32_e32 v63, v63, v58
	v_exp_f32_e32 v39, v35
	v_sub_f32_e32 v35, v40, v58
	v_add_f32_e32 v121, v122, v121
	v_exp_f32_e32 v62, v62
	v_mul_f32_e32 v63, 0x3fb8aa3b, v63
	v_sub_f32_e32 v64, v64, v58
	v_mul_f32_e32 v35, 0x3fb8aa3b, v35
	v_add_f32_e32 v59, v123, v121
	v_exp_f32_e32 v63, v63
	v_mul_f32_e32 v64, 0x3fb8aa3b, v64
	v_sub_f32_e32 v65, v65, v58
	v_exp_f32_e32 v40, v35
	v_sub_f32_e32 v35, v41, v58
	v_add_f32_e32 v59, v60, v59
	v_exp_f32_e32 v64, v64
	v_mul_f32_e32 v65, 0x3fb8aa3b, v65
	v_sub_f32_e32 v34, v34, v58
	v_mul_f32_e32 v35, 0x3fb8aa3b, v35
	v_add_f32_e32 v59, v61, v59
	v_exp_f32_e32 v65, v65
	v_mul_f32_e32 v34, 0x3fb8aa3b, v34
	v_exp_f32_e32 v41, v35
	v_sub_f32_e32 v35, v42, v58
	v_add_f32_e32 v59, v62, v59
	v_exp_f32_e32 v121, v34
	v_mul_f32_e32 v35, 0x3fb8aa3b, v35
	v_add_f32_e32 v59, v63, v59
	v_exp_f32_e32 v42, v35
	v_sub_f32_e32 v35, v43, v58
	v_add_f32_e32 v59, v64, v59
	v_mul_f32_e32 v35, 0x3fb8aa3b, v35
	v_add_f32_e32 v59, v65, v59
	v_exp_f32_e32 v43, v35
	v_sub_f32_e32 v35, v44, v58
	v_add_f32_e32 v34, v121, v59
	v_mul_f32_e32 v35, 0x3fb8aa3b, v35
	v_add_f32_e32 v34, v124, v34
	v_exp_f32_e32 v44, v35
	v_sub_f32_e32 v35, v45, v58
	v_add_f32_e32 v34, v125, v34
	v_mul_f32_e32 v35, 0x3fb8aa3b, v35
	v_add_f32_e32 v34, v126, v34
	v_exp_f32_e32 v45, v35
	v_sub_f32_e32 v35, v46, v58
	v_add_f32_e32 v34, v38, v34
	v_mul_f32_e32 v35, 0x3fb8aa3b, v35
	v_add_f32_e32 v34, v39, v34
	v_exp_f32_e32 v46, v35
	v_sub_f32_e32 v35, v47, v58
	v_add_f32_e32 v34, v40, v34
	v_mul_f32_e32 v35, 0x3fb8aa3b, v35
	v_add_f32_e32 v34, v41, v34
	v_exp_f32_e32 v47, v35
	v_sub_f32_e32 v35, v48, v58
	v_add_f32_e32 v34, v42, v34
	v_mul_f32_e32 v35, 0x3fb8aa3b, v35
	v_add_f32_e32 v34, v43, v34
	v_exp_f32_e32 v48, v35
	v_sub_f32_e32 v35, v49, v58
	v_add_f32_e32 v34, v44, v34
	v_mul_f32_e32 v35, 0x3fb8aa3b, v35
	v_add_f32_e32 v34, v45, v34
	v_exp_f32_e32 v49, v35
	v_add_f32_e32 v34, v46, v34
	v_add_f32_e32 v34, v47, v34
	v_mul_f32_e32 v120, 0x3fb8aa3b, v120
	v_add_f32_e32 v34, v48, v34
	v_add_f32_e32 v59, v49, v34
	v_exp_f32_e32 v34, v120
	v_cvt_pk_f16_f32 v36, v54, v55
	v_cvt_pk_f16_f32 v37, v56, v57
	v_fmac_f32_e32 v59, v119, v34
	v_pk_mul_f32 v[2:3], v[2:3], v[34:35] op_sel_hi:[1,0]
	v_pk_mul_f32 v[4:5], v[4:5], v[34:35] op_sel_hi:[1,0]
	v_pk_mul_f32 v[6:7], v[6:7], v[34:35] op_sel_hi:[1,0]
	v_pk_mul_f32 v[8:9], v[8:9], v[34:35] op_sel_hi:[1,0]
	v_pk_mul_f32 v[10:11], v[10:11], v[34:35] op_sel_hi:[1,0]
	v_pk_mul_f32 v[12:13], v[12:13], v[34:35] op_sel_hi:[1,0]
	v_pk_mul_f32 v[14:15], v[14:15], v[34:35] op_sel_hi:[1,0]
	v_pk_mul_f32 v[16:17], v[16:17], v[34:35] op_sel_hi:[1,0]
	v_pk_mul_f32 v[18:19], v[18:19], v[34:35] op_sel_hi:[1,0]
	v_pk_mul_f32 v[20:21], v[20:21], v[34:35] op_sel_hi:[1,0]
	v_pk_mul_f32 v[22:23], v[22:23], v[34:35] op_sel_hi:[1,0]
	v_pk_mul_f32 v[24:25], v[24:25], v[34:35] op_sel_hi:[1,0]
	v_pk_mul_f32 v[26:27], v[26:27], v[34:35] op_sel_hi:[1,0]
	v_pk_mul_f32 v[28:29], v[28:29], v[34:35] op_sel_hi:[1,0]
	v_pk_mul_f32 v[30:31], v[30:31], v[34:35] op_sel_hi:[1,0]
	v_pk_mul_f32 v[32:33], v[32:33], v[34:35] op_sel_hi:[1,0]
	v_cvt_pk_f16_f32 v34, v50, v51
	v_cvt_pk_f16_f32 v35, v52, v53
	s_waitcnt vmcnt(8)
	s_nop 0
	v_mfma_f32_32x32x16_f16 v[2:17], v[110:113], v[34:37], v[2:17]
	v_mfma_f32_32x32x16_f16 v[18:33], v[106:109], v[34:37], v[18:33]
	v_cvt_pk_f16_f32 v34, v122, v123
	v_cvt_pk_f16_f32 v35, v60, v61
	v_cvt_pk_f16_f32 v36, v62, v63
	v_cvt_pk_f16_f32 v37, v64, v65
	s_nop 1
	v_mfma_f32_32x32x16_f16 v[2:17], v[102:105], v[34:37], v[2:17]
	v_mfma_f32_32x32x16_f16 v[18:33], v[98:101], v[34:37], v[18:33]
	v_cvt_pk_f16_f32 v34, v121, v124
	v_cvt_pk_f16_f32 v35, v125, v126
	v_cvt_pk_f16_f32 v36, v38, v39
	v_cvt_pk_f16_f32 v37, v40, v41
	s_nop 0
	v_mfma_f32_32x32x16_f16 v[2:17], v[94:97], v[34:37], v[2:17]
	v_mfma_f32_32x32x16_f16 v[18:33], v[90:93], v[34:37], v[18:33]
	v_cvt_pk_f16_f32 v34, v42, v43
	v_cvt_pk_f16_f32 v35, v44, v45
	v_cvt_pk_f16_f32 v36, v46, v47
	v_cvt_pk_f16_f32 v37, v48, v49
	s_nop 1
	v_mfma_f32_32x32x16_f16 v[2:17], v[86:89], v[34:37], v[2:17]
	v_mfma_f32_32x32x16_f16 v[18:33], v[82:85], v[34:37], v[18:33]
	s_add_u32 s28, s2, s0
	s_addc_u32 s29, s3, s1
	s_add_u32 s28, s28, 0x18806000
	s_addc_u32 s29, s29, 0
	global_load_dwordx4 v[110:113], v184, s[28:29]
	global_load_dwordx4 v[102:105], v184, s[28:29] offset:1024
	global_load_dwordx4 v[106:109], v184, s[28:29] offset:2048
	global_load_dwordx4 v[98:101], v184, s[28:29] offset:3072
	s_add_u32 s28, s28, 0x8000
	s_addc_u32 s29, s29, 0
	global_load_dwordx4 v[94:97], v184, s[28:29]
	global_load_dwordx4 v[86:89], v184, s[28:29] offset:1024
	global_load_dwordx4 v[90:93], v184, s[28:29] offset:2048
	global_load_dwordx4 v[82:85], v184, s[28:29] offset:3072
	s_cmp_eq_u32 s0, 0x80000
	s_cbranch_scc0 .LBB0_329
; #define MFMA32(a, b, c) __builtin_amdgcn_mfma_f32_32x32x16_f16((a), (b), (c), 0, 0, 0)
; DI int otid() { int t = threadIdx.x; asm volatile("" : "+v"(t)); return t; }
; DI int crow(int i, int h) { return (i & 3) + 8 * (i >> 2) + 4 * h; }
; template <int HD, int BIAS, bool FULL>
; DI void attn_block(const bf16_t* Kb, int ktb, const bf16_t* Vb, int vtb, int koff, int kpos0, int qp, float slope, const float* rel,
;                    const bf16x8 (&qf)[HD / 16], f32x16 (&o)[HD / 32], float& m, float& l) {
;     ...
;     constexpr bool VTOP = HD == 64;
;     const int lane = otid() & 63, h = lane >> 5;
;     const int kbeg = FULL ? 0 : koff, kend = FULL ? 64 : koff + 16;
;     const int s0 = FULL ? 0 : (koff >> 4);
;     int dq = kpos0 + 4 * h - qp; asm volatile("" : "+v"(dq));
;     bf16x8 kreg[NKT][KSQ];
; #pragma unroll
;     for (int kt = 0; kt < NKT; ++kt)
; #pragma unroll
;         for (int ks = 0; ks < KSQ; ++ks) kreg[kt][ks] = *(const bf16x8*)(Kb + (size_t)kt * ktb + ks * 512 + lane * 8);
;     constexpr int NS = FULL ? 4 : 1;
;     bf16x8 vreg[DT][NS];
;     auto loadV = [&]() {
; #pragma unroll
;         for (int si = 0; si < NS; ++si)
; #pragma unroll
;             for (int dt = 0; dt < DT; ++dt) { const int s = FULL ? si : s0; vreg[dt][si] = *(const bf16x8*)(Vb + (size_t)(s >> 1) * vtb + dt * 1024 + (s & 1) * 512 + lane * 8); }
;     };
;     if (VTOP) loadV();
;     __builtin_amdgcn_sched_barrier(0);
;     f32x16 st[NKT];
; #pragma unroll
;     for (int kt = 0; kt < NKT; ++kt) {
; #pragma unroll
;         for (int i = 0; i < 16; ++i) st[kt][i] = 0.f;
; #pragma unroll
;         for (int ks = 0; ks < KSQ; ++ks) st[kt] = MFMA32(kreg[kt][ks], qf[ks], st[kt]);
;     }
;     __builtin_amdgcn_sched_barrier(0);
;     if (!VTOP) loadV();
;     float mx = -1e30f;
; #pragma unroll
;     for (int kt = 0; kt < NKT; ++kt)
; #pragma unroll
;         for (int i = 0; i < 16; ++i) {
;             const int key = kt * 32 + crow(i, h);
;             float s = st[kt][i];
;             const int dk = dq + (kt * 32 + (i & 3) + 8 * (i >> 2));
;             if (BIAS == 1) s -= slope * (float)(dk < 0 ? -dk : dk);
;             if (BIAS == 2) { int d = dk < -256 ? -256 : (dk > 256 ? 256 : dk); s += rel[d + 256]; }
;             if (!FULL) { if (key < kbeg || key >= kend) s = -1e30f; }
	s_waitcnt vmcnt(0)
	v_mov_b32_e32 v34, v176
	s_lshl_b32 s0, s96, 10
	v_lshrrev_b32_e32 v35, 3, v34
	v_and_b32_e32 v63, 4, v35
	v_or_b32_e32 v35, s97, v117
	v_lshlrev_b32_e32 v34, 4, v34
	v_sub_u32_e32 v62, v63, v35
	v_and_b32_e32 v38, 0x3f0, v34
	global_load_dwordx4 v[34:37], v38, s[66:67]
	global_load_dwordx4 v[82:85], v38, s[66:67] offset:1024
	global_load_dwordx4 v[86:89], v38, s[66:67] offset:2048
	global_load_dwordx4 v[90:93], v38, s[66:67] offset:3072
	s_add_u32 s0, s57, s0
	s_addc_u32 s1, s60, 0
	global_load_dwordx4 v[50:53], v38, s[0:1]
	global_load_dwordx4 v[54:57], v38, s[0:1] offset:2048
	s_waitcnt vmcnt(5)
	v_mfma_f32_32x32x16_f16 v[34:49], v[34:37], v[78:81], 0
	s_waitcnt vmcnt(4)
	v_mfma_f32_32x32x16_f16 v[34:49], v[82:85], v[74:77], v[34:49]
	s_waitcnt vmcnt(3)
	v_mfma_f32_32x32x16_f16 v[34:49], v[86:89], v[66:69], v[34:49]
	s_waitcnt vmcnt(2)
	v_mfma_f32_32x32x16_f16 v[34:49], v[90:93], v[70:73], v[34:49]
	v_cmp_gt_u32_e64 s[0:1], s97, v63
	v_cmp_le_u32_e32 vcc, s97, v63
	v_mov_b32_e32 v60, 0xf149f2ca
	v_mov_b32_e32 v61, 0xf149f2ca
	s_and_saveexec_b64 s[2:3], vcc
	s_cbranch_execz .LBB0_332
	v_med3_i32 v61, v62, s45, v186
	v_lshl_add_u32 v61, v61, 2, s61
	ds_read_b32 v61, v61 offset:1024
	s_waitcnt lgkmcnt(0)
	s_nop 1
	v_add_f32_e32 v61, v34, v61
